# attention unit prologue: the eight K fragment reads of the first QK^T issued up front into separate registers with counted lgkmcnt waits (was serialised through one register quad)
# baseline (speedup 1.0000x reference)
.LBB0_220:
	s_lshl_b32 s8, s21, 1
	s_add_i32 s9, s8, s37
	s_cmp_lt_i32 s9, 0
	s_cbranch_scc1 .LBB0_226
	ds_read_b128 v[0:3], v192
	ds_read_b128 v[32:35], v192 offset:32
	ds_read_b128 v[16:19], v192 offset:8704
	ds_read_b128 v[36:39], v192 offset:8736
	ds_read_b128 v[40:43], v192 offset:64
	ds_read_b128 v[44:47], v192 offset:8768
	ds_read_b128 v[48:51], v192 offset:96
	ds_read_b128 v[52:55], v192 offset:8800
	s_cmp_gt_u32 s9, 2
	s_waitcnt lgkmcnt(7)
	v_mfma_f32_32x32x16_bf16 v[0:15], v[0:3], v[112:115], 0
	s_waitcnt lgkmcnt(6)
	v_mfma_f32_32x32x16_bf16 v[0:15], v[32:35], v[116:119], v[0:15]
	s_waitcnt lgkmcnt(5)
	v_mfma_f32_32x32x16_bf16 v[16:31], v[16:19], v[112:115], 0
	s_waitcnt lgkmcnt(4)
	v_mfma_f32_32x32x16_bf16 v[16:31], v[36:39], v[116:119], v[16:31]
	s_waitcnt lgkmcnt(3)
	v_mfma_f32_32x32x16_bf16 v[0:15], v[40:43], v[120:123], v[0:15]
	s_waitcnt lgkmcnt(2)
	v_mfma_f32_32x32x16_bf16 v[16:31], v[44:47], v[120:123], v[16:31]
	s_waitcnt lgkmcnt(1)
	v_mfma_f32_32x32x16_bf16 v[0:15], v[48:51], v[124:127], v[0:15]
	s_waitcnt lgkmcnt(0)
	v_mfma_f32_32x32x16_bf16 v[16:31], v[52:55], v[124:127], v[16:31]
	s_cbranch_scc1 .LBB0_223
	v_lshl_or_b32 v32, s9, 8, v195
	v_sub_u32_e32 v56, v193, v32
	ds_read2_b32 v[32:33], v56 offset0:192 offset1:193
	ds_read2_b32 v[34:35], v56 offset0:194 offset1:195
	ds_read2_b32 v[36:37], v56 offset0:200 offset1:201
	ds_read2_b32 v[38:39], v56 offset0:202 offset1:203
	ds_read2_b32 v[40:41], v56 offset0:208 offset1:209
	ds_read2_b32 v[42:43], v56 offset0:210 offset1:211
	ds_read2_b32 v[44:45], v56 offset0:216 offset1:217
	ds_read2_b32 v[46:47], v56 offset0:218 offset1:219
	ds_read2_b32 v[48:49], v56 offset0:224 offset1:225
	ds_read2_b32 v[50:51], v56 offset0:226 offset1:227
	ds_read2_b32 v[52:53], v56 offset0:232 offset1:233
	ds_read2_b32 v[54:55], v56 offset0:234 offset1:235
	s_waitcnt lgkmcnt(4)
	v_pk_add_f32 v[14:15], v[14:15], v[46:47]
	v_pk_add_f32 v[12:13], v[12:13], v[44:45]
	v_pk_add_f32 v[10:11], v[10:11], v[42:43]
	v_pk_add_f32 v[8:9], v[8:9], v[40:41]
	ds_read2_b32 v[40:41], v56 offset0:240 offset1:241
	ds_read2_b32 v[42:43], v56 offset0:242 offset1:243
	ds_read2_b32 v[44:45], v56 offset0:248 offset1:249
	ds_read2_b32 v[46:47], v56 offset0:250 offset1:251
	v_pk_add_f32 v[6:7], v[6:7], v[38:39]
	v_pk_add_f32 v[4:5], v[4:5], v[36:37]
	v_pk_add_f32 v[2:3], v[2:3], v[34:35]
	v_pk_add_f32 v[0:1], v[0:1], v[32:33]
	s_waitcnt lgkmcnt(0)
	v_pk_add_f32 v[30:31], v[30:31], v[46:47]
	v_pk_add_f32 v[28:29], v[28:29], v[44:45]
	v_pk_add_f32 v[26:27], v[26:27], v[42:43]
	v_pk_add_f32 v[24:25], v[24:25], v[40:41]
	v_pk_add_f32 v[22:23], v[22:23], v[54:55]
	v_pk_add_f32 v[20:21], v[20:21], v[52:53]
	v_pk_add_f32 v[18:19], v[18:19], v[50:51]
	v_pk_add_f32 v[16:17], v[16:17], v[48:49]
